# ln2 loop-edge edit: selected experts enumerated with s_ff1 over a 16-bit mask instead of a 16-iteration readlane/compare/branch scan
# baseline (speedup 1.0000x reference)
.LBB0_1400:
	v_cmp_lt_i32_e32 vcc, -1, v76
	s_nop 1
	s_and_b32 s12, vcc_lo, 0xffff
.Lg_scan0:
	s_cmp_eq_u32 s12, 0
	s_cbranch_scc1 .LBB0_1393
	s_ff1_i32_b32 s7, s12
	s_bitset0_b32 s12, s7
	v_readlane_b32 s2, v76, s7
	s_nop 1
	v_mov_b32_e32 v40, s2
	v_lshlrev_b64 v[94:95], 10, v[40:41]
	v_lshl_add_u64 v[94:95], v[36:37], 0, v[94:95]
	global_load_dword v96, v[94:95], off
	global_load_dword v97, v[94:95], off offset:256
	global_load_dword v98, v[94:95], off offset:512
	global_load_dword v99, v[94:95], off offset:768
	s_cmp_eq_u32 s12, 0
	s_cbranch_scc1 .Lg_cons1
	s_ff1_i32_b32 s7, s12
	s_bitset0_b32 s12, s7
	v_readlane_b32 s2, v76, s7
	s_nop 1
	v_mov_b32_e32 v40, s2
	v_lshlrev_b64 v[94:95], 10, v[40:41]
	v_lshl_add_u64 v[94:95], v[36:37], 0, v[94:95]
	global_load_dword v100, v[94:95], off
	global_load_dword v101, v[94:95], off offset:256
	global_load_dword v102, v[94:95], off offset:512
	global_load_dword v103, v[94:95], off offset:768
	s_cmp_eq_u32 s12, 0
	s_cbranch_scc1 .Lg_cons2
	s_ff1_i32_b32 s7, s12
	s_bitset0_b32 s12, s7
	v_readlane_b32 s2, v76, s7
	s_nop 1
	v_mov_b32_e32 v40, s2
	v_lshlrev_b64 v[94:95], 10, v[40:41]
	v_lshl_add_u64 v[94:95], v[36:37], 0, v[94:95]
	global_load_dword v104, v[94:95], off
	global_load_dword v105, v[94:95], off offset:256
	global_load_dword v106, v[94:95], off offset:512
	global_load_dword v107, v[94:95], off offset:768
	s_cmp_eq_u32 s12, 0
	s_cbranch_scc1 .Lg_cons3
	s_ff1_i32_b32 s7, s12
	s_bitset0_b32 s12, s7
	v_readlane_b32 s2, v76, s7
	s_nop 1
	v_mov_b32_e32 v40, s2
	v_lshlrev_b64 v[94:95], 10, v[40:41]
	v_lshl_add_u64 v[94:95], v[36:37], 0, v[94:95]
	global_load_dword v108, v[94:95], off
	global_load_dword v109, v[94:95], off offset:256
	global_load_dword v110, v[94:95], off offset:512
	global_load_dword v111, v[94:95], off offset:768
.Lg_cons4:
	s_waitcnt vmcnt(12)
	v_cvt_f32_fp8_e32 v78, v96
	v_cvt_f32_fp8_sdwa v79, v96 src0_sel:BYTE_1
	v_cvt_f32_fp8_sdwa v80, v96 src0_sel:BYTE_2
	v_cvt_f32_fp8_sdwa v81, v96 src0_sel:BYTE_3
	v_cvt_f32_fp8_e32 v82, v97
	v_cvt_f32_fp8_sdwa v83, v97 src0_sel:BYTE_1
	v_cvt_f32_fp8_sdwa v84, v97 src0_sel:BYTE_2
	v_cvt_f32_fp8_sdwa v85, v97 src0_sel:BYTE_3
	v_cvt_f32_fp8_e32 v86, v98
	v_cvt_f32_fp8_sdwa v87, v98 src0_sel:BYTE_1
	v_cvt_f32_fp8_sdwa v88, v98 src0_sel:BYTE_2
	v_cvt_f32_fp8_sdwa v89, v98 src0_sel:BYTE_3
	v_cvt_f32_fp8_e32 v90, v99
	v_cvt_f32_fp8_sdwa v91, v99 src0_sel:BYTE_1
	v_cvt_f32_fp8_sdwa v92, v99 src0_sel:BYTE_2
	v_cvt_f32_fp8_sdwa v93, v99 src0_sel:BYTE_3
	v_pk_fma_f32 v[64:65], v[78:79], s[6:7], v[64:65] op_sel_hi:[1,0,1]
	v_pk_fma_f32 v[62:63], v[80:81], s[6:7], v[62:63] op_sel_hi:[1,0,1]
	v_pk_fma_f32 v[60:61], v[82:83], s[6:7], v[60:61] op_sel_hi:[1,0,1]
	v_pk_fma_f32 v[58:59], v[84:85], s[6:7], v[58:59] op_sel_hi:[1,0,1]
	v_pk_fma_f32 v[56:57], v[86:87], s[6:7], v[56:57] op_sel_hi:[1,0,1]
	v_pk_fma_f32 v[54:55], v[88:89], s[6:7], v[54:55] op_sel_hi:[1,0,1]
	v_pk_fma_f32 v[50:51], v[90:91], s[6:7], v[50:51] op_sel_hi:[1,0,1]
	v_pk_fma_f32 v[52:53], v[92:93], s[6:7], v[52:53] op_sel_hi:[1,0,1]
	s_waitcnt vmcnt(8)
	v_cvt_f32_fp8_e32 v78, v100
	v_cvt_f32_fp8_sdwa v79, v100 src0_sel:BYTE_1
	v_cvt_f32_fp8_sdwa v80, v100 src0_sel:BYTE_2
	v_cvt_f32_fp8_sdwa v81, v100 src0_sel:BYTE_3
	v_cvt_f32_fp8_e32 v82, v101
	v_cvt_f32_fp8_sdwa v83, v101 src0_sel:BYTE_1
	v_cvt_f32_fp8_sdwa v84, v101 src0_sel:BYTE_2
	v_cvt_f32_fp8_sdwa v85, v101 src0_sel:BYTE_3
	v_cvt_f32_fp8_e32 v86, v102
	v_cvt_f32_fp8_sdwa v87, v102 src0_sel:BYTE_1
	v_cvt_f32_fp8_sdwa v88, v102 src0_sel:BYTE_2
	v_cvt_f32_fp8_sdwa v89, v102 src0_sel:BYTE_3
	v_cvt_f32_fp8_e32 v90, v103
	v_cvt_f32_fp8_sdwa v91, v103 src0_sel:BYTE_1
	v_cvt_f32_fp8_sdwa v92, v103 src0_sel:BYTE_2
	v_cvt_f32_fp8_sdwa v93, v103 src0_sel:BYTE_3
	v_pk_fma_f32 v[64:65], v[78:79], s[6:7], v[64:65] op_sel_hi:[1,0,1]
	v_pk_fma_f32 v[62:63], v[80:81], s[6:7], v[62:63] op_sel_hi:[1,0,1]
	v_pk_fma_f32 v[60:61], v[82:83], s[6:7], v[60:61] op_sel_hi:[1,0,1]
	v_pk_fma_f32 v[58:59], v[84:85], s[6:7], v[58:59] op_sel_hi:[1,0,1]
	v_pk_fma_f32 v[56:57], v[86:87], s[6:7], v[56:57] op_sel_hi:[1,0,1]
	v_pk_fma_f32 v[54:55], v[88:89], s[6:7], v[54:55] op_sel_hi:[1,0,1]
	v_pk_fma_f32 v[50:51], v[90:91], s[6:7], v[50:51] op_sel_hi:[1,0,1]
	v_pk_fma_f32 v[52:53], v[92:93], s[6:7], v[52:53] op_sel_hi:[1,0,1]
	s_waitcnt vmcnt(4)
	v_cvt_f32_fp8_e32 v78, v104
	v_cvt_f32_fp8_sdwa v79, v104 src0_sel:BYTE_1
	v_cvt_f32_fp8_sdwa v80, v104 src0_sel:BYTE_2
	v_cvt_f32_fp8_sdwa v81, v104 src0_sel:BYTE_3
	v_cvt_f32_fp8_e32 v82, v105
	v_cvt_f32_fp8_sdwa v83, v105 src0_sel:BYTE_1
	v_cvt_f32_fp8_sdwa v84, v105 src0_sel:BYTE_2
	v_cvt_f32_fp8_sdwa v85, v105 src0_sel:BYTE_3
	v_cvt_f32_fp8_e32 v86, v106
	v_cvt_f32_fp8_sdwa v87, v106 src0_sel:BYTE_1
	v_cvt_f32_fp8_sdwa v88, v106 src0_sel:BYTE_2
	v_cvt_f32_fp8_sdwa v89, v106 src0_sel:BYTE_3
	v_cvt_f32_fp8_e32 v90, v107
	v_cvt_f32_fp8_sdwa v91, v107 src0_sel:BYTE_1
	v_cvt_f32_fp8_sdwa v92, v107 src0_sel:BYTE_2
	v_cvt_f32_fp8_sdwa v93, v107 src0_sel:BYTE_3
	v_pk_fma_f32 v[64:65], v[78:79], s[6:7], v[64:65] op_sel_hi:[1,0,1]
	v_pk_fma_f32 v[62:63], v[80:81], s[6:7], v[62:63] op_sel_hi:[1,0,1]
	v_pk_fma_f32 v[60:61], v[82:83], s[6:7], v[60:61] op_sel_hi:[1,0,1]
	v_pk_fma_f32 v[58:59], v[84:85], s[6:7], v[58:59] op_sel_hi:[1,0,1]
	v_pk_fma_f32 v[56:57], v[86:87], s[6:7], v[56:57] op_sel_hi:[1,0,1]
	v_pk_fma_f32 v[54:55], v[88:89], s[6:7], v[54:55] op_sel_hi:[1,0,1]
	v_pk_fma_f32 v[50:51], v[90:91], s[6:7], v[50:51] op_sel_hi:[1,0,1]
	v_pk_fma_f32 v[52:53], v[92:93], s[6:7], v[52:53] op_sel_hi:[1,0,1]
	s_waitcnt vmcnt(0)
	v_cvt_f32_fp8_e32 v78, v108
	v_cvt_f32_fp8_sdwa v79, v108 src0_sel:BYTE_1
	v_cvt_f32_fp8_sdwa v80, v108 src0_sel:BYTE_2
	v_cvt_f32_fp8_sdwa v81, v108 src0_sel:BYTE_3
	v_cvt_f32_fp8_e32 v82, v109
	v_cvt_f32_fp8_sdwa v83, v109 src0_sel:BYTE_1
	v_cvt_f32_fp8_sdwa v84, v109 src0_sel:BYTE_2
	v_cvt_f32_fp8_sdwa v85, v109 src0_sel:BYTE_3
	v_cvt_f32_fp8_e32 v86, v110
	v_cvt_f32_fp8_sdwa v87, v110 src0_sel:BYTE_1
	v_cvt_f32_fp8_sdwa v88, v110 src0_sel:BYTE_2
	v_cvt_f32_fp8_sdwa v89, v110 src0_sel:BYTE_3
	v_cvt_f32_fp8_e32 v90, v111
	v_cvt_f32_fp8_sdwa v91, v111 src0_sel:BYTE_1
	v_cvt_f32_fp8_sdwa v92, v111 src0_sel:BYTE_2
	v_cvt_f32_fp8_sdwa v93, v111 src0_sel:BYTE_3
	v_pk_fma_f32 v[64:65], v[78:79], s[6:7], v[64:65] op_sel_hi:[1,0,1]
	v_pk_fma_f32 v[62:63], v[80:81], s[6:7], v[62:63] op_sel_hi:[1,0,1]
	v_pk_fma_f32 v[60:61], v[82:83], s[6:7], v[60:61] op_sel_hi:[1,0,1]
	v_pk_fma_f32 v[58:59], v[84:85], s[6:7], v[58:59] op_sel_hi:[1,0,1]
	v_pk_fma_f32 v[56:57], v[86:87], s[6:7], v[56:57] op_sel_hi:[1,0,1]
	v_pk_fma_f32 v[54:55], v[88:89], s[6:7], v[54:55] op_sel_hi:[1,0,1]
	v_pk_fma_f32 v[50:51], v[90:91], s[6:7], v[50:51] op_sel_hi:[1,0,1]
	v_pk_fma_f32 v[52:53], v[92:93], s[6:7], v[52:53] op_sel_hi:[1,0,1]
	s_branch .Lg_scan0
